# v37 plus: the adaLN (latency-chained) waves of P1 run at raised priority (s_setprio 3) against the conversion waves that share their SIMDs
# speedup vs baseline: 1.0040x; 1.0034x over previous
; #define INP(i) ((const float*)(const GASP float*)kargs()[(i)])
; #define WSP ((unsigned char*)(GASP unsigned char*)kargs()[N_IN + 1])
; __device__ __forceinline__ void phase_ada(const Frame& F, int item0, int istride) {
;     unsigned char* ws = WSP; const bf16* SC = (const bf16*)(ws + WS_SC); float* MOD = (float*)(ws + WS_MOD);
;     const int r = F.lane & 15, kq = F.lane >> 4;
;     for (int item = item0; item < 1152; item += istride) { const int l = item / 288, n0 = (item % 288) * 64;
;         const float* W = INP(I_WADA) + (size_t)l * 2048 * NMODW + (size_t)(kq * 8) * NMODW + n0 + 4 * r; const bf16* sp = SC + (size_t)r * D + kq * 8;
;         f32x4 acc[9][4];
; #pragma unroll
;         for (int bt = 0; bt < 9; ++bt)
; #pragma unroll
;             for (int e = 0; e < 4; ++e) acc[bt][e] = (f32x4){0.f, 0.f, 0.f, 0.f};
;         f32x4 w[8];
; #pragma unroll
;         for (int i = 0; i < 8; ++i) w[i] = __builtin_nontemporal_load((const f32x4*)(W + (size_t)i * NMODW));
; __device__ __forceinline__ void phase_ada_conv(const Frame& F) {
;     ...
;         if (F.wave < nA) phase_ada(F, pair * 9 + (odd ? 5 + F.wave : F.wave), 1152);
.LBB0_300:
	s_andn2_b64 vcc, exec, s[10:11]
	s_cbranch_vccnz .LBB0_308
	s_add_i32 s10, s85, 5
	s_and_b64 s[6:7], s[6:7], exec
	s_mul_i32 s40, s40, 9
	s_cselect_b32 s6, s85, s10
	s_add_i32 s18, s6, s40
	s_mov_b64 s[6:7], s[0:1]
	s_cmpk_gt_i32 s18, 0x47f
	s_cbranch_scc1 .LBB0_308
	s_setprio 3
	s_load_dwordx2 s[10:11], s[6:7], 0x138
	v_ashrrev_i32_e32 v0, 1, v197
	v_and_b32_e32 v3, 15, v197
	v_and_b32_e32 v0, -8, v0
	s_mov_b32 s21, 0x12000
	v_ashrrev_i32_e32 v1, 31, v0
	v_mad_i64_i32 v[184:185], s[6:7], v0, s21, 0
	v_mov_b32_e32 v187, 0
	v_and_b32_e32 v4, -16, v197
	v_lshlrev_b32_e32 v186, 12, v3
	s_waitcnt lgkmcnt(0)
	s_add_u32 s19, s10, 0x3c400000
	v_lshlrev_b32_e32 v2, 2, v3
	v_ashrrev_i32_e32 v5, 31, v4
	v_mul_u32_u24_e32 v6, 0x12000, v3
	v_or_b32_e32 v7, 0x80, v3
	s_movk_i32 s6, 0x84
	v_lshl_add_u64 v[0:1], v[0:1], 1, v[186:187]
	s_addc_u32 s20, s11, 0
	v_cmp_gt_u32_e64 s[6:7], s6, v7
	v_lshl_add_u64 v[188:189], s[10:11], 0, v[0:1]
	v_lshlrev_b32_e32 v190, 2, v2
	v_mov_b32_e32 v191, v187
	s_mov_b32 s11, 0
	s_mov_b32 s22, 0x24000
	s_mov_b32 s23, 0x36000
	s_mov_b32 s26, 0x48000
	s_mov_b32 s27, 0x5a000
	s_mov_b32 s28, 0x6c000
	s_mov_b32 s29, 0x7e000
	s_mov_b32 s30, 0x3c300000
	s_mov_b32 s31, 0x3c310000
	s_mov_b32 s33, 0x3c320000
	s_mov_b32 s34, 0x3c330000
	s_mov_b32 s35, 0x3c340000
	s_mov_b32 s36, 0x3c350000
	s_mov_b32 s37, 0x3c360000
	s_mov_b32 s38, 0x3c370000
	s_mov_b32 s39, 0x3c380000
	v_lshlrev_b64 v[192:193], 2, v[4:5]
	v_lshlrev_b32_e32 v186, 2, v6
	s_mov_b32 s40, 0x480000
	s_mov_b32 s41, 0x900000
	s_mov_b32 s42, 0xd80000
	s_mov_b32 s43, 0x1200000
	s_mov_b32 s44, 0x1680000
	s_mov_b32 s45, 0x1b00000
	s_mov_b32 s46, 0x1f80000
	s_mov_b64 s[12:13], 0x2400000
	s_branch .LBB0_304

; __device__ __forceinline__ unsigned xb_ld(unsigned* p)              { return __hip_atomic_load(p, __ATOMIC_RELAXED, __HIP_MEMORY_SCOPE_AGENT); }
; __device__ __forceinline__ bool xb_leader(int wid) { return wid == 0 && __builtin_amdgcn_mbcnt_hi(~0u, __builtin_amdgcn_mbcnt_lo(~0u, 0u)) == 0u; }
; __device__ __forceinline__ void xcd_barrier_complete(unsigned* bar, unsigned x, unsigned& nloc, unsigned& nx) {
;     const unsigned G = gridDim.x * gridDim.y * gridDim.z;
;     unsigned sum, cnt, mine, sp = 0u;
;     for (;;) {
;         sum = 0u; cnt = 0u; mine = 0u;
; #pragma unroll
;         for (unsigned j = 0; j < 16; ++j) { const unsigned c = xb_ld(&bar[XB_XCNT(j)]); sum += c; cnt += (c > 0u) ? 1u : 0u; mine = (j == x) ? c : mine; }
; __device__ __forceinline__ void xcd_barrier(const XcdBarrier& b) {
;     asm volatile("s_waitcnt vmcnt(0)" ::: "memory");
;     __syncthreads();
;     if (xb_leader(b.wid)) {
;         unsigned* bar = b.bar;
;         __builtin_amdgcn_s_waitcnt(0);
;         unsigned nloc = b.st[0], nx = b.st[1];
;         if (nloc == 0u) { xcd_barrier_complete(bar, b.x, nloc, nx); b.st[0] = nloc; b.st[1] = nx; }
.LBB0_308:
	s_setprio 0
	s_cmp_gt_i32 s81, 2
	s_cselect_b64 s[6:7], -1, 0
	s_and_b64 s[6:7], s[8:9], s[6:7]
	s_andn2_b64 vcc, exec, s[6:7]
	s_cbranch_vccnz .LBB0_364
	s_waitcnt vmcnt(0)
	s_and_b64 vcc, exec, s[4:5]
	s_waitcnt lgkmcnt(0)
	s_barrier
	s_cbranch_vccnz .LBB0_363
	v_mbcnt_hi_u32_b32 v0, -1, v196
	v_cmp_eq_u32_e32 vcc, 0, v0
	s_and_saveexec_b64 s[6:7], vcc
	s_cbranch_execz .LBB0_362
	s_add_i32 s8, 0, 0x20160
	v_mov_b32_e32 v0, s8
	s_waitcnt vmcnt(0) expcnt(0) lgkmcnt(0)
	ds_read_b32 v2, v0
	s_add_i32 s8, 0, 0x20164
	v_mov_b32_e32 v0, s8
	ds_read_b32 v0, v0
	s_waitcnt lgkmcnt(1)
	v_cmp_ne_u32_e32 vcc, 0, v2
	s_cbranch_vccnz .LBB0_326
	s_load_dwordx2 s[12:13], s[0:1], 0x148
	s_load_dword s11, s[0:1], 0x150
	s_add_u32 s8, s24, 0x4200
	s_addc_u32 s9, s25, 0
	s_add_u32 s10, s24, 0x4400
	s_waitcnt lgkmcnt(0)
	s_mul_i32 s33, s13, s12
	s_mul_i32 s33, s33, s11
	s_addc_u32 s11, s25, 0
	s_add_u32 s12, s24, 0x4500
	s_addc_u32 s13, s25, 0
	s_add_u32 s14, s24, 0x4600
	s_addc_u32 s15, s25, 0
	s_add_u32 s16, s24, 0x4700
	s_addc_u32 s17, s25, 0
	s_add_u32 s18, s24, 0x4800
	s_addc_u32 s19, s25, 0
	s_add_u32 s20, s24, 0x4900
	s_addc_u32 s21, s25, 0
	s_add_u32 s22, s24, 0x4a00
	s_addc_u32 s23, s25, 0
	s_add_u32 s26, s24, 0x4b00
	s_addc_u32 s27, s25, 0
	s_add_u32 s28, s24, 0x4c00
	s_addc_u32 s29, s25, 0
	s_add_u32 s30, s24, 0x4d00
	s_addc_u32 s31, s25, 0
	s_add_u32 s34, s24, 0x4e00
	s_addc_u32 s35, s25, 0
	s_add_u32 s36, s24, 0x4f00
	s_addc_u32 s37, s25, 0
	s_add_u32 s38, s24, 0x5000
	s_addc_u32 s39, s25, 0
	s_add_u32 s40, s24, 0x5100
	s_addc_u32 s41, s25, 0
	s_add_u32 s42, s24, 0x5200
	s_addc_u32 s43, s25, 0
	s_add_u32 s44, s24, 0x5300
	s_addc_u32 s45, s25, 0
	s_mov_b32 s52, 1
	v_mov_b32_e32 v16, 0
	s_branch .LBB0_314
